# GEMM K loops: priority raised after the first MFMA and dropped again after the last LDS write (MFMA slot 27) instead of at the barrier
# baseline (speedup 1.0000x reference)
.Lgq_c:
	ds_read_b128 v[114:117], v188 offset:16384
	ds_read_b128 v[118:121], v188 offset:16896
	ds_read_b128 v[156:159], v188 offset:20480
	ds_read_b128 v[160:163], v188 offset:20992
	ds_read_b128 v[122:125], v112
	ds_read_b128 v[126:129], v112 offset:2048
	s_waitcnt lgkmcnt(1)
	v_mfma_f32_16x16x32_bf16 v[66:69], v[114:117], v[122:125], v[66:69]
	s_setprio 2
	global_load_dwordx4 v[62:65], v216, s[0:1] offset:256
	v_mfma_f32_16x16x32_bf16 v[58:61], v[118:121], v[122:125], v[58:61]
	s_waitcnt vmcnt(8)
	ds_write_b128 v110, v[224:227] offset:32768
	v_mfma_f32_16x16x32_bf16 v[54:57], v[156:159], v[122:125], v[54:57]
	v_mfma_f32_16x16x32_bf16 v[50:53], v[160:163], v[122:125], v[50:53]
	global_load_dwordx4 v[70:73], v217, s[0:1] offset:256
	s_waitcnt lgkmcnt(1)
	v_mfma_f32_16x16x32_bf16 v[46:49], v[114:117], v[126:129], v[46:49]
	ds_read_b128 v[180:183], v112 offset:4096
	ds_read_b128 v[184:187], v112 offset:6144
	v_mfma_f32_16x16x32_bf16 v[42:45], v[118:121], v[126:129], v[42:45]
	s_waitcnt vmcnt(8)
	ds_write_b128 v110, v[228:231] offset:36864
	v_mfma_f32_16x16x32_bf16 v[38:41], v[156:159], v[126:129], v[38:41]
	global_load_dwordx4 v[74:77], v218, s[0:1] offset:256
	v_mfma_f32_16x16x32_bf16 v[34:37], v[160:163], v[126:129], v[34:37]
	s_waitcnt lgkmcnt(2)
	v_mfma_f32_16x16x32_bf16 v[30:33], v[114:117], v[180:183], v[30:33]
	ds_read_b128 v[164:167], v189 offset:16384
	ds_read_b128 v[168:171], v189 offset:16896
	v_mfma_f32_16x16x32_bf16 v[26:29], v[118:121], v[180:183], v[26:29]
	global_load_dwordx4 v[78:81], v219, s[0:1] offset:256
	v_mfma_f32_16x16x32_bf16 v[22:25], v[156:159], v[180:183], v[22:25]
	ds_read_b128 v[172:175], v189 offset:20480
	ds_read_b128 v[176:179], v189 offset:20992
	v_mfma_f32_16x16x32_bf16 v[18:21], v[160:163], v[180:183], v[18:21]
	s_waitcnt vmcnt(9)
	ds_write_b128 v110, v[232:235] offset:40960
	s_waitcnt lgkmcnt(6)
	v_mfma_f32_16x16x32_bf16 v[14:17], v[114:117], v[184:187], v[14:17]
	ds_read_b128 v[122:125], v113
	ds_read_b128 v[126:129], v113 offset:2048
	v_mfma_f32_16x16x32_bf16 v[10:13], v[118:121], v[184:187], v[10:13]
	global_load_dwordx4 v[82:85], v216, s[6:7] offset:256
	v_mfma_f32_16x16x32_bf16 v[6:9], v[156:159], v[184:187], v[6:9]
	s_waitcnt vmcnt(9)
	ds_write_b128 v110, v[236:239] offset:45056
	v_mfma_f32_16x16x32_bf16 v[2:5], v[160:163], v[184:187], v[2:5]
	s_waitcnt lgkmcnt(2)
	v_mfma_f32_16x16x32_bf16 v[66:69], v[164:167], v[122:125], v[66:69]
	global_load_dwordx4 v[86:89], v217, s[6:7] offset:256
	v_mfma_f32_16x16x32_bf16 v[58:61], v[168:171], v[122:125], v[58:61]
	s_waitcnt vmcnt(9)
	ds_write_b128 v190, v[240:243] offset:49168
	v_mfma_f32_16x16x32_bf16 v[54:57], v[172:175], v[122:125], v[54:57]
	v_mfma_f32_16x16x32_bf16 v[50:53], v[176:179], v[122:125], v[50:53]
	global_load_dwordx4 v[90:93], v218, s[6:7] offset:256
	s_waitcnt lgkmcnt(2)
	v_mfma_f32_16x16x32_bf16 v[46:49], v[164:167], v[126:129], v[46:49]
	ds_read_b128 v[180:183], v113 offset:4096
	ds_read_b128 v[184:187], v113 offset:6144
	v_mfma_f32_16x16x32_bf16 v[42:45], v[168:171], v[126:129], v[42:45]
	s_waitcnt vmcnt(9)
	ds_write_b128 v190, v[244:247] offset:53264
	v_mfma_f32_16x16x32_bf16 v[38:41], v[172:175], v[126:129], v[38:41]
	global_load_dwordx4 v[94:97], v219, s[6:7] offset:256
	v_mfma_f32_16x16x32_bf16 v[34:37], v[176:179], v[126:129], v[34:37]
	s_waitcnt lgkmcnt(2)
	v_mfma_f32_16x16x32_bf16 v[30:33], v[164:167], v[180:183], v[30:33]
	s_waitcnt vmcnt(9)
	ds_write_b128 v190, v[248:251] offset:57360
	v_mfma_f32_16x16x32_bf16 v[26:29], v[168:171], v[180:183], v[26:29]
	v_mfma_f32_16x16x32_bf16 v[22:25], v[172:175], v[180:183], v[22:25]
	v_mfma_f32_16x16x32_bf16 v[18:21], v[176:179], v[180:183], v[18:21]
	s_waitcnt vmcnt(8)
	ds_write_b128 v190, v[252:255] offset:61456
	s_setprio 0
	s_waitcnt lgkmcnt(3)
	v_mfma_f32_16x16x32_bf16 v[14:17], v[164:167], v[184:187], v[14:17]
	v_mfma_f32_16x16x32_bf16 v[10:13], v[168:171], v[184:187], v[10:13]
	v_mfma_f32_16x16x32_bf16 v[6:9], v[172:175], v[184:187], v[6:9]
	v_mfma_f32_16x16x32_bf16 v[2:5], v[176:179], v[184:187], v[2:5]
	s_setprio 0
	s_waitcnt lgkmcnt(0)
	s_barrier
	s_add_u32 s0, s0, 0x80
	s_addc_u32 s1, s1, 0
	s_add_u32 s6, s6, 0x80
	s_addc_u32 s7, s7, 0
	ds_read_b128 v[114:117], v188 offset:49168
	ds_read_b128 v[118:121], v188 offset:49680
	ds_read_b128 v[156:159], v188 offset:53264
	ds_read_b128 v[160:163], v188 offset:53776
	ds_read_b128 v[122:125], v112 offset:32768
	ds_read_b128 v[126:129], v112 offset:34816
	s_waitcnt lgkmcnt(1)
	v_mfma_f32_16x16x32_bf16 v[66:69], v[114:117], v[122:125], v[66:69]
	s_setprio 2
	global_load_dwordx4 v[224:227], v216, s[0:1] offset:256
	v_mfma_f32_16x16x32_bf16 v[58:61], v[118:121], v[122:125], v[58:61]
	s_waitcnt vmcnt(8)
	ds_write_b128 v110, v[62:65]
	v_mfma_f32_16x16x32_bf16 v[54:57], v[156:159], v[122:125], v[54:57]
	v_mfma_f32_16x16x32_bf16 v[50:53], v[160:163], v[122:125], v[50:53]
	global_load_dwordx4 v[228:231], v217, s[0:1] offset:256
	s_waitcnt lgkmcnt(1)
	v_mfma_f32_16x16x32_bf16 v[46:49], v[114:117], v[126:129], v[46:49]
	ds_read_b128 v[180:183], v112 offset:36864
	ds_read_b128 v[184:187], v112 offset:38912
	v_mfma_f32_16x16x32_bf16 v[42:45], v[118:121], v[126:129], v[42:45]
	s_waitcnt vmcnt(8)
	ds_write_b128 v110, v[70:73] offset:4096
	v_mfma_f32_16x16x32_bf16 v[38:41], v[156:159], v[126:129], v[38:41]
	global_load_dwordx4 v[232:235], v218, s[0:1] offset:256
	v_mfma_f32_16x16x32_bf16 v[34:37], v[160:163], v[126:129], v[34:37]
	s_waitcnt lgkmcnt(2)
	v_mfma_f32_16x16x32_bf16 v[30:33], v[114:117], v[180:183], v[30:33]
	ds_read_b128 v[164:167], v189 offset:49168
	ds_read_b128 v[168:171], v189 offset:49680
	v_mfma_f32_16x16x32_bf16 v[26:29], v[118:121], v[180:183], v[26:29]
	global_load_dwordx4 v[236:239], v219, s[0:1] offset:256
	v_mfma_f32_16x16x32_bf16 v[22:25], v[156:159], v[180:183], v[22:25]
	ds_read_b128 v[172:175], v189 offset:53264
	ds_read_b128 v[176:179], v189 offset:53776
	v_mfma_f32_16x16x32_bf16 v[18:21], v[160:163], v[180:183], v[18:21]
	s_waitcnt vmcnt(9)
	ds_write_b128 v110, v[74:77] offset:8192
	s_waitcnt lgkmcnt(6)
	v_mfma_f32_16x16x32_bf16 v[14:17], v[114:117], v[184:187], v[14:17]
	ds_read_b128 v[122:125], v113 offset:32768
	ds_read_b128 v[126:129], v113 offset:34816
	v_mfma_f32_16x16x32_bf16 v[10:13], v[118:121], v[184:187], v[10:13]
	global_load_dwordx4 v[240:243], v216, s[6:7] offset:256
	v_mfma_f32_16x16x32_bf16 v[6:9], v[156:159], v[184:187], v[6:9]
	s_waitcnt vmcnt(9)
	ds_write_b128 v110, v[78:81] offset:12288
	v_mfma_f32_16x16x32_bf16 v[2:5], v[160:163], v[184:187], v[2:5]
	s_waitcnt lgkmcnt(2)
	v_mfma_f32_16x16x32_bf16 v[66:69], v[164:167], v[122:125], v[66:69]
	global_load_dwordx4 v[244:247], v217, s[6:7] offset:256
	v_mfma_f32_16x16x32_bf16 v[58:61], v[168:171], v[122:125], v[58:61]
	s_waitcnt vmcnt(9)
	ds_write_b128 v190, v[82:85] offset:16384
	v_mfma_f32_16x16x32_bf16 v[54:57], v[172:175], v[122:125], v[54:57]
	v_mfma_f32_16x16x32_bf16 v[50:53], v[176:179], v[122:125], v[50:53]
	global_load_dwordx4 v[248:251], v218, s[6:7] offset:256
	s_waitcnt lgkmcnt(2)
	v_mfma_f32_16x16x32_bf16 v[46:49], v[164:167], v[126:129], v[46:49]
	ds_read_b128 v[180:183], v113 offset:36864
	ds_read_b128 v[184:187], v113 offset:38912
	v_mfma_f32_16x16x32_bf16 v[42:45], v[168:171], v[126:129], v[42:45]
	s_waitcnt vmcnt(9)
	ds_write_b128 v190, v[86:89] offset:20480
	v_mfma_f32_16x16x32_bf16 v[38:41], v[172:175], v[126:129], v[38:41]
	global_load_dwordx4 v[252:255], v219, s[6:7] offset:256
	v_mfma_f32_16x16x32_bf16 v[34:37], v[176:179], v[126:129], v[34:37]
	s_waitcnt lgkmcnt(2)
	v_mfma_f32_16x16x32_bf16 v[30:33], v[164:167], v[180:183], v[30:33]
	s_waitcnt vmcnt(9)
	ds_write_b128 v190, v[90:93] offset:24576
	v_mfma_f32_16x16x32_bf16 v[26:29], v[168:171], v[180:183], v[26:29]
	v_mfma_f32_16x16x32_bf16 v[22:25], v[172:175], v[180:183], v[22:25]
	v_mfma_f32_16x16x32_bf16 v[18:21], v[176:179], v[180:183], v[18:21]
	s_waitcnt vmcnt(8)
	ds_write_b128 v190, v[94:97] offset:28672
	s_setprio 0
	s_waitcnt lgkmcnt(3)
	v_mfma_f32_16x16x32_bf16 v[14:17], v[164:167], v[184:187], v[14:17]
	v_mfma_f32_16x16x32_bf16 v[10:13], v[168:171], v[184:187], v[10:13]
	v_mfma_f32_16x16x32_bf16 v[6:9], v[172:175], v[184:187], v[6:9]
	v_mfma_f32_16x16x32_bf16 v[2:5], v[176:179], v[184:187], v[2:5]
	s_setprio 0
	s_waitcnt lgkmcnt(0)
	s_barrier
	s_add_u32 s0, s0, 0x80
	s_addc_u32 s1, s1, 0
	s_add_u32 s6, s6, 0x80
	s_addc_u32 s7, s7, 0
	s_sub_i32 vcc_lo, vcc_lo, 1
	s_cmp_lg_u32 vcc_lo, 0
	s_cbranch_scc1 .Lgq_c
	ds_read_b128 v[114:117], v188 offset:16384
	ds_read_b128 v[118:121], v188 offset:16896
	ds_read_b128 v[156:159], v188 offset:20480
	ds_read_b128 v[160:163], v188 offset:20992
	ds_read_b128 v[122:125], v112
	ds_read_b128 v[126:129], v112 offset:2048
	s_waitcnt lgkmcnt(1)
	v_mfma_f32_16x16x32_bf16 v[66:69], v[114:117], v[122:125], v[66:69]
	s_setprio 2
	v_mfma_f32_16x16x32_bf16 v[58:61], v[118:121], v[122:125], v[58:61]
	s_waitcnt vmcnt(7)
	ds_write_b128 v110, v[224:227] offset:32768
	v_mfma_f32_16x16x32_bf16 v[54:57], v[156:159], v[122:125], v[54:57]
	v_mfma_f32_16x16x32_bf16 v[50:53], v[160:163], v[122:125], v[50:53]
	s_waitcnt lgkmcnt(1)
	v_mfma_f32_16x16x32_bf16 v[46:49], v[114:117], v[126:129], v[46:49]
	ds_read_b128 v[180:183], v112 offset:4096
	ds_read_b128 v[184:187], v112 offset:6144
	v_mfma_f32_16x16x32_bf16 v[42:45], v[118:121], v[126:129], v[42:45]
	s_waitcnt vmcnt(6)
	ds_write_b128 v110, v[228:231] offset:36864
	v_mfma_f32_16x16x32_bf16 v[38:41], v[156:159], v[126:129], v[38:41]
	v_mfma_f32_16x16x32_bf16 v[34:37], v[160:163], v[126:129], v[34:37]
	s_waitcnt lgkmcnt(2)
	v_mfma_f32_16x16x32_bf16 v[30:33], v[114:117], v[180:183], v[30:33]
	ds_read_b128 v[164:167], v189 offset:16384
	ds_read_b128 v[168:171], v189 offset:16896
	v_mfma_f32_16x16x32_bf16 v[26:29], v[118:121], v[180:183], v[26:29]
	v_mfma_f32_16x16x32_bf16 v[22:25], v[156:159], v[180:183], v[22:25]
	ds_read_b128 v[172:175], v189 offset:20480
	ds_read_b128 v[176:179], v189 offset:20992
	v_mfma_f32_16x16x32_bf16 v[18:21], v[160:163], v[180:183], v[18:21]
	s_waitcnt vmcnt(5)
	ds_write_b128 v110, v[232:235] offset:40960
	s_waitcnt lgkmcnt(6)
	v_mfma_f32_16x16x32_bf16 v[14:17], v[114:117], v[184:187], v[14:17]
	ds_read_b128 v[122:125], v113
	ds_read_b128 v[126:129], v113 offset:2048
	v_mfma_f32_16x16x32_bf16 v[10:13], v[118:121], v[184:187], v[10:13]
	v_mfma_f32_16x16x32_bf16 v[6:9], v[156:159], v[184:187], v[6:9]
	s_waitcnt vmcnt(4)
	ds_write_b128 v110, v[236:239] offset:45056
	v_mfma_f32_16x16x32_bf16 v[2:5], v[160:163], v[184:187], v[2:5]
	s_waitcnt lgkmcnt(2)
	v_mfma_f32_16x16x32_bf16 v[66:69], v[164:167], v[122:125], v[66:69]
	v_mfma_f32_16x16x32_bf16 v[58:61], v[168:171], v[122:125], v[58:61]
	s_waitcnt vmcnt(3)
	ds_write_b128 v190, v[240:243] offset:49168
	v_mfma_f32_16x16x32_bf16 v[54:57], v[172:175], v[122:125], v[54:57]
	v_mfma_f32_16x16x32_bf16 v[50:53], v[176:179], v[122:125], v[50:53]
	s_waitcnt lgkmcnt(2)
	v_mfma_f32_16x16x32_bf16 v[46:49], v[164:167], v[126:129], v[46:49]
	ds_read_b128 v[180:183], v113 offset:4096
	ds_read_b128 v[184:187], v113 offset:6144
	v_mfma_f32_16x16x32_bf16 v[42:45], v[168:171], v[126:129], v[42:45]
	s_waitcnt vmcnt(2)
	ds_write_b128 v190, v[244:247] offset:53264
	v_mfma_f32_16x16x32_bf16 v[38:41], v[172:175], v[126:129], v[38:41]
	v_mfma_f32_16x16x32_bf16 v[34:37], v[176:179], v[126:129], v[34:37]
	s_waitcnt lgkmcnt(2)
	v_mfma_f32_16x16x32_bf16 v[30:33], v[164:167], v[180:183], v[30:33]
	s_waitcnt vmcnt(1)
	ds_write_b128 v190, v[248:251] offset:57360
	v_mfma_f32_16x16x32_bf16 v[26:29], v[168:171], v[180:183], v[26:29]
	v_mfma_f32_16x16x32_bf16 v[22:25], v[172:175], v[180:183], v[22:25]
	v_mfma_f32_16x16x32_bf16 v[18:21], v[176:179], v[180:183], v[18:21]
	s_waitcnt vmcnt(0)
	ds_write_b128 v190, v[252:255] offset:61456
	s_setprio 0
	s_waitcnt lgkmcnt(3)
	v_mfma_f32_16x16x32_bf16 v[14:17], v[164:167], v[184:187], v[14:17]
	v_mfma_f32_16x16x32_bf16 v[10:13], v[168:171], v[184:187], v[10:13]
	v_mfma_f32_16x16x32_bf16 v[6:9], v[172:175], v[184:187], v[6:9]
	v_mfma_f32_16x16x32_bf16 v[2:5], v[176:179], v[184:187], v[2:5]
	s_waitcnt lgkmcnt(0)
	s_barrier
	ds_read_b128 v[114:117], v188 offset:49168
	ds_read_b128 v[118:121], v188 offset:49680
	ds_read_b128 v[156:159], v188 offset:53264
	ds_read_b128 v[160:163], v188 offset:53776
	ds_read_b128 v[122:125], v112 offset:32768
	ds_read_b128 v[126:129], v112 offset:34816
	s_waitcnt lgkmcnt(1)
	v_mfma_f32_16x16x32_bf16 v[66:69], v[114:117], v[122:125], v[66:69]
	s_setprio 2
	v_mfma_f32_16x16x32_bf16 v[58:61], v[118:121], v[122:125], v[58:61]
	v_mfma_f32_16x16x32_bf16 v[54:57], v[156:159], v[122:125], v[54:57]
	v_mfma_f32_16x16x32_bf16 v[50:53], v[160:163], v[122:125], v[50:53]
	s_waitcnt lgkmcnt(0)
	v_mfma_f32_16x16x32_bf16 v[46:49], v[114:117], v[126:129], v[46:49]
	ds_read_b128 v[180:183], v112 offset:36864
	ds_read_b128 v[184:187], v112 offset:38912
	v_mfma_f32_16x16x32_bf16 v[42:45], v[118:121], v[126:129], v[42:45]
	v_mfma_f32_16x16x32_bf16 v[38:41], v[156:159], v[126:129], v[38:41]
	v_mfma_f32_16x16x32_bf16 v[34:37], v[160:163], v[126:129], v[34:37]
	s_waitcnt lgkmcnt(1)
	v_mfma_f32_16x16x32_bf16 v[30:33], v[114:117], v[180:183], v[30:33]
	ds_read_b128 v[164:167], v189 offset:49168
	ds_read_b128 v[168:171], v189 offset:49680
	v_mfma_f32_16x16x32_bf16 v[26:29], v[118:121], v[180:183], v[26:29]
	v_mfma_f32_16x16x32_bf16 v[22:25], v[156:159], v[180:183], v[22:25]
	ds_read_b128 v[172:175], v189 offset:53264
	ds_read_b128 v[176:179], v189 offset:53776
	v_mfma_f32_16x16x32_bf16 v[18:21], v[160:163], v[180:183], v[18:21]
	s_waitcnt lgkmcnt(4)
	v_mfma_f32_16x16x32_bf16 v[14:17], v[114:117], v[184:187], v[14:17]
	ds_read_b128 v[122:125], v113 offset:32768
	ds_read_b128 v[126:129], v113 offset:34816
	v_mfma_f32_16x16x32_bf16 v[10:13], v[118:121], v[184:187], v[10:13]
	v_mfma_f32_16x16x32_bf16 v[6:9], v[156:159], v[184:187], v[6:9]
	v_mfma_f32_16x16x32_bf16 v[2:5], v[160:163], v[184:187], v[2:5]
	s_waitcnt lgkmcnt(1)
	v_mfma_f32_16x16x32_bf16 v[66:69], v[164:167], v[122:125], v[66:69]
	v_mfma_f32_16x16x32_bf16 v[58:61], v[168:171], v[122:125], v[58:61]
	v_mfma_f32_16x16x32_bf16 v[54:57], v[172:175], v[122:125], v[54:57]
	v_mfma_f32_16x16x32_bf16 v[50:53], v[176:179], v[122:125], v[50:53]
	s_waitcnt lgkmcnt(0)
	v_mfma_f32_16x16x32_bf16 v[46:49], v[164:167], v[126:129], v[46:49]
	ds_read_b128 v[180:183], v113 offset:36864
	ds_read_b128 v[184:187], v113 offset:38912
	v_mfma_f32_16x16x32_bf16 v[42:45], v[168:171], v[126:129], v[42:45]
	v_mfma_f32_16x16x32_bf16 v[38:41], v[172:175], v[126:129], v[38:41]
	v_mfma_f32_16x16x32_bf16 v[34:37], v[176:179], v[126:129], v[34:37]
	s_waitcnt lgkmcnt(1)
	v_mfma_f32_16x16x32_bf16 v[30:33], v[164:167], v[180:183], v[30:33]
	v_mfma_f32_16x16x32_bf16 v[26:29], v[168:171], v[180:183], v[26:29]
	v_mfma_f32_16x16x32_bf16 v[22:25], v[172:175], v[180:183], v[22:25]
	v_mfma_f32_16x16x32_bf16 v[18:21], v[176:179], v[180:183], v[18:21]
	s_setprio 0
	s_waitcnt lgkmcnt(0)
	v_mfma_f32_16x16x32_bf16 v[14:17], v[164:167], v[184:187], v[14:17]
	v_mfma_f32_16x16x32_bf16 v[10:13], v[168:171], v[184:187], v[10:13]
	v_mfma_f32_16x16x32_bf16 v[6:9], v[172:175], v[184:187], v[6:9]
	v_mfma_f32_16x16x32_bf16 v[2:5], v[176:179], v[184:187], v[2:5]
	s_setprio 0
	s_barrier

.Lgq_o:
	ds_read_b128 v[114:117], v188 offset:16384
	ds_read_b128 v[122:125], v188 offset:16896
	ds_read_b128 v[126:129], v188 offset:20480
	ds_read_b128 v[156:159], v188 offset:20992
	ds_read_b128 v[118:121], v112
	ds_read_b128 v[160:163], v112 offset:2048
	s_waitcnt lgkmcnt(1)
	v_mfma_f32_16x16x32_bf16 v[94:97], v[114:117], v[118:121], v[94:97]
	s_setprio 2
	global_load_dwordx4 v[2:5], v216, s[10:11] offset:256
	v_mfma_f32_16x16x32_bf16 v[90:93], v[122:125], v[118:121], v[90:93]
	s_waitcnt vmcnt(8)
	ds_write_b128 v108, v[224:227] offset:32768
	v_mfma_f32_16x16x32_bf16 v[86:89], v[126:129], v[118:121], v[86:89]
	v_mfma_f32_16x16x32_bf16 v[82:85], v[156:159], v[118:121], v[82:85]
	global_load_dwordx4 v[6:9], v217, s[10:11] offset:256
	s_waitcnt lgkmcnt(1)
	v_mfma_f32_16x16x32_bf16 v[78:81], v[114:117], v[160:163], v[78:81]
	ds_read_b128 v[180:183], v112 offset:4096
	ds_read_b128 v[184:187], v112 offset:6144
	v_mfma_f32_16x16x32_bf16 v[74:77], v[122:125], v[160:163], v[74:77]
	s_waitcnt vmcnt(8)
	ds_write_b128 v108, v[228:231] offset:36864
	v_mfma_f32_16x16x32_bf16 v[70:73], v[126:129], v[160:163], v[70:73]
	global_load_dwordx4 v[10:13], v218, s[10:11] offset:256
	v_mfma_f32_16x16x32_bf16 v[66:69], v[156:159], v[160:163], v[66:69]
	s_waitcnt lgkmcnt(2)
	v_mfma_f32_16x16x32_bf16 v[62:65], v[114:117], v[180:183], v[62:65]
	ds_read_b128 v[164:167], v189 offset:16384
	ds_read_b128 v[168:171], v189 offset:16896
	v_mfma_f32_16x16x32_bf16 v[58:61], v[122:125], v[180:183], v[58:61]
	global_load_dwordx4 v[14:17], v219, s[10:11] offset:256
	v_mfma_f32_16x16x32_bf16 v[54:57], v[126:129], v[180:183], v[54:57]
	ds_read_b128 v[172:175], v189 offset:20480
	ds_read_b128 v[176:179], v189 offset:20992
	v_mfma_f32_16x16x32_bf16 v[50:53], v[156:159], v[180:183], v[50:53]
	s_waitcnt vmcnt(9)
	ds_write_b128 v108, v[232:235] offset:40960
	s_waitcnt lgkmcnt(6)
	v_mfma_f32_16x16x32_bf16 v[46:49], v[114:117], v[184:187], v[46:49]
	ds_read_b128 v[118:121], v113
	ds_read_b128 v[160:163], v113 offset:2048
	v_mfma_f32_16x16x32_bf16 v[42:45], v[122:125], v[184:187], v[42:45]
	global_load_dwordx4 v[18:21], v216, s[28:29] offset:256
	v_mfma_f32_16x16x32_bf16 v[38:41], v[126:129], v[184:187], v[38:41]
	s_waitcnt vmcnt(9)
	ds_write_b128 v108, v[236:239] offset:45056
	v_mfma_f32_16x16x32_bf16 v[34:37], v[156:159], v[184:187], v[34:37]
	s_waitcnt lgkmcnt(2)
	v_mfma_f32_16x16x32_bf16 v[94:97], v[164:167], v[118:121], v[94:97]
	global_load_dwordx4 v[22:25], v217, s[28:29] offset:256
	v_mfma_f32_16x16x32_bf16 v[90:93], v[168:171], v[118:121], v[90:93]
	s_waitcnt vmcnt(9)
	ds_write_b128 v190, v[240:243] offset:49168
	v_mfma_f32_16x16x32_bf16 v[86:89], v[172:175], v[118:121], v[86:89]
	v_mfma_f32_16x16x32_bf16 v[82:85], v[176:179], v[118:121], v[82:85]
	global_load_dwordx4 v[26:29], v218, s[28:29] offset:256
	s_waitcnt lgkmcnt(2)
	v_mfma_f32_16x16x32_bf16 v[78:81], v[164:167], v[160:163], v[78:81]
	ds_read_b128 v[180:183], v113 offset:4096
	ds_read_b128 v[184:187], v113 offset:6144
	v_mfma_f32_16x16x32_bf16 v[74:77], v[168:171], v[160:163], v[74:77]
	s_waitcnt vmcnt(9)
	ds_write_b128 v190, v[244:247] offset:53264
	v_mfma_f32_16x16x32_bf16 v[70:73], v[172:175], v[160:163], v[70:73]
	global_load_dwordx4 v[30:33], v219, s[28:29] offset:256
	v_mfma_f32_16x16x32_bf16 v[66:69], v[176:179], v[160:163], v[66:69]
	s_waitcnt lgkmcnt(2)
	v_mfma_f32_16x16x32_bf16 v[62:65], v[164:167], v[180:183], v[62:65]
	s_waitcnt vmcnt(9)
	ds_write_b128 v190, v[248:251] offset:57360
	v_mfma_f32_16x16x32_bf16 v[58:61], v[168:171], v[180:183], v[58:61]
	v_mfma_f32_16x16x32_bf16 v[54:57], v[172:175], v[180:183], v[54:57]
	v_mfma_f32_16x16x32_bf16 v[50:53], v[176:179], v[180:183], v[50:53]
	s_waitcnt vmcnt(8)
	ds_write_b128 v190, v[252:255] offset:61456
	s_setprio 0
	s_waitcnt lgkmcnt(3)
	v_mfma_f32_16x16x32_bf16 v[46:49], v[164:167], v[184:187], v[46:49]
	v_mfma_f32_16x16x32_bf16 v[42:45], v[168:171], v[184:187], v[42:45]
	v_mfma_f32_16x16x32_bf16 v[38:41], v[172:175], v[184:187], v[38:41]
	v_mfma_f32_16x16x32_bf16 v[34:37], v[176:179], v[184:187], v[34:37]
	s_setprio 0
	s_waitcnt lgkmcnt(0)
	s_barrier
	s_add_u32 s10, s10, 0x80
	s_addc_u32 s11, s11, 0
	s_add_u32 s28, s28, 0x80
	s_addc_u32 s29, s29, 0
	ds_read_b128 v[114:117], v188 offset:49168
	ds_read_b128 v[122:125], v188 offset:49680
	ds_read_b128 v[126:129], v188 offset:53264
	ds_read_b128 v[156:159], v188 offset:53776
	ds_read_b128 v[118:121], v112 offset:32768
	ds_read_b128 v[160:163], v112 offset:34816
	s_waitcnt lgkmcnt(1)
	v_mfma_f32_16x16x32_bf16 v[94:97], v[114:117], v[118:121], v[94:97]
	s_setprio 2
	global_load_dwordx4 v[224:227], v216, s[10:11] offset:256
	v_mfma_f32_16x16x32_bf16 v[90:93], v[122:125], v[118:121], v[90:93]
	s_waitcnt vmcnt(8)
	ds_write_b128 v108, v[2:5]
	v_mfma_f32_16x16x32_bf16 v[86:89], v[126:129], v[118:121], v[86:89]
	v_mfma_f32_16x16x32_bf16 v[82:85], v[156:159], v[118:121], v[82:85]
	global_load_dwordx4 v[228:231], v217, s[10:11] offset:256
	s_waitcnt lgkmcnt(1)
	v_mfma_f32_16x16x32_bf16 v[78:81], v[114:117], v[160:163], v[78:81]
	ds_read_b128 v[180:183], v112 offset:36864
	ds_read_b128 v[184:187], v112 offset:38912
	v_mfma_f32_16x16x32_bf16 v[74:77], v[122:125], v[160:163], v[74:77]
	s_waitcnt vmcnt(8)
	ds_write_b128 v108, v[6:9] offset:4096
	v_mfma_f32_16x16x32_bf16 v[70:73], v[126:129], v[160:163], v[70:73]
	global_load_dwordx4 v[232:235], v218, s[10:11] offset:256
	v_mfma_f32_16x16x32_bf16 v[66:69], v[156:159], v[160:163], v[66:69]
	s_waitcnt lgkmcnt(2)
	v_mfma_f32_16x16x32_bf16 v[62:65], v[114:117], v[180:183], v[62:65]
	ds_read_b128 v[164:167], v189 offset:49168
	ds_read_b128 v[168:171], v189 offset:49680
	v_mfma_f32_16x16x32_bf16 v[58:61], v[122:125], v[180:183], v[58:61]
	global_load_dwordx4 v[236:239], v219, s[10:11] offset:256
	v_mfma_f32_16x16x32_bf16 v[54:57], v[126:129], v[180:183], v[54:57]
	ds_read_b128 v[172:175], v189 offset:53264
	ds_read_b128 v[176:179], v189 offset:53776
	v_mfma_f32_16x16x32_bf16 v[50:53], v[156:159], v[180:183], v[50:53]
	s_waitcnt vmcnt(9)
	ds_write_b128 v108, v[10:13] offset:8192
	s_waitcnt lgkmcnt(6)
	v_mfma_f32_16x16x32_bf16 v[46:49], v[114:117], v[184:187], v[46:49]
	ds_read_b128 v[118:121], v113 offset:32768
	ds_read_b128 v[160:163], v113 offset:34816
	v_mfma_f32_16x16x32_bf16 v[42:45], v[122:125], v[184:187], v[42:45]
	global_load_dwordx4 v[240:243], v216, s[28:29] offset:256
	v_mfma_f32_16x16x32_bf16 v[38:41], v[126:129], v[184:187], v[38:41]
	s_waitcnt vmcnt(9)
	ds_write_b128 v108, v[14:17] offset:12288
	v_mfma_f32_16x16x32_bf16 v[34:37], v[156:159], v[184:187], v[34:37]
	s_waitcnt lgkmcnt(2)
	v_mfma_f32_16x16x32_bf16 v[94:97], v[164:167], v[118:121], v[94:97]
	global_load_dwordx4 v[244:247], v217, s[28:29] offset:256
	v_mfma_f32_16x16x32_bf16 v[90:93], v[168:171], v[118:121], v[90:93]
	s_waitcnt vmcnt(9)
	ds_write_b128 v190, v[18:21] offset:16384
	v_mfma_f32_16x16x32_bf16 v[86:89], v[172:175], v[118:121], v[86:89]
	v_mfma_f32_16x16x32_bf16 v[82:85], v[176:179], v[118:121], v[82:85]
	global_load_dwordx4 v[248:251], v218, s[28:29] offset:256
	s_waitcnt lgkmcnt(2)
	v_mfma_f32_16x16x32_bf16 v[78:81], v[164:167], v[160:163], v[78:81]
	ds_read_b128 v[180:183], v113 offset:36864
	ds_read_b128 v[184:187], v113 offset:38912
	v_mfma_f32_16x16x32_bf16 v[74:77], v[168:171], v[160:163], v[74:77]
	s_waitcnt vmcnt(9)
	ds_write_b128 v190, v[22:25] offset:20480
	v_mfma_f32_16x16x32_bf16 v[70:73], v[172:175], v[160:163], v[70:73]
	global_load_dwordx4 v[252:255], v219, s[28:29] offset:256
	v_mfma_f32_16x16x32_bf16 v[66:69], v[176:179], v[160:163], v[66:69]
	s_waitcnt lgkmcnt(2)
	v_mfma_f32_16x16x32_bf16 v[62:65], v[164:167], v[180:183], v[62:65]
	s_waitcnt vmcnt(9)
	ds_write_b128 v190, v[26:29] offset:24576
	v_mfma_f32_16x16x32_bf16 v[58:61], v[168:171], v[180:183], v[58:61]
	v_mfma_f32_16x16x32_bf16 v[54:57], v[172:175], v[180:183], v[54:57]
	v_mfma_f32_16x16x32_bf16 v[50:53], v[176:179], v[180:183], v[50:53]
	s_waitcnt vmcnt(8)
	ds_write_b128 v190, v[30:33] offset:28672
	s_setprio 0
	s_waitcnt lgkmcnt(3)
	v_mfma_f32_16x16x32_bf16 v[46:49], v[164:167], v[184:187], v[46:49]
	v_mfma_f32_16x16x32_bf16 v[42:45], v[168:171], v[184:187], v[42:45]
	v_mfma_f32_16x16x32_bf16 v[38:41], v[172:175], v[184:187], v[38:41]
	v_mfma_f32_16x16x32_bf16 v[34:37], v[176:179], v[184:187], v[34:37]
	s_setprio 0
	s_waitcnt lgkmcnt(0)
	s_barrier
	s_add_u32 s10, s10, 0x80
	s_addc_u32 s11, s11, 0
	s_add_u32 s28, s28, 0x80
	s_addc_u32 s29, s29, 0
	s_sub_i32 vcc_lo, vcc_lo, 1
	s_cmp_lg_u32 vcc_lo, 0
	s_cbranch_scc1 .Lgq_o
	ds_read_b128 v[114:117], v188 offset:16384
	ds_read_b128 v[122:125], v188 offset:16896
	ds_read_b128 v[126:129], v188 offset:20480
	ds_read_b128 v[156:159], v188 offset:20992
	ds_read_b128 v[118:121], v112
	ds_read_b128 v[160:163], v112 offset:2048
	s_waitcnt lgkmcnt(1)
	v_mfma_f32_16x16x32_bf16 v[94:97], v[114:117], v[118:121], v[94:97]
	s_setprio 2
	v_mfma_f32_16x16x32_bf16 v[90:93], v[122:125], v[118:121], v[90:93]
	s_waitcnt vmcnt(7)
	ds_write_b128 v108, v[224:227] offset:32768
	v_mfma_f32_16x16x32_bf16 v[86:89], v[126:129], v[118:121], v[86:89]
	v_mfma_f32_16x16x32_bf16 v[82:85], v[156:159], v[118:121], v[82:85]
	s_waitcnt lgkmcnt(1)
	v_mfma_f32_16x16x32_bf16 v[78:81], v[114:117], v[160:163], v[78:81]
	ds_read_b128 v[180:183], v112 offset:4096
	ds_read_b128 v[184:187], v112 offset:6144
	v_mfma_f32_16x16x32_bf16 v[74:77], v[122:125], v[160:163], v[74:77]
	s_waitcnt vmcnt(6)
	ds_write_b128 v108, v[228:231] offset:36864
	v_mfma_f32_16x16x32_bf16 v[70:73], v[126:129], v[160:163], v[70:73]
	v_mfma_f32_16x16x32_bf16 v[66:69], v[156:159], v[160:163], v[66:69]
	s_waitcnt lgkmcnt(2)
	v_mfma_f32_16x16x32_bf16 v[62:65], v[114:117], v[180:183], v[62:65]
	ds_read_b128 v[164:167], v189 offset:16384
	ds_read_b128 v[168:171], v189 offset:16896
	v_mfma_f32_16x16x32_bf16 v[58:61], v[122:125], v[180:183], v[58:61]
	v_mfma_f32_16x16x32_bf16 v[54:57], v[126:129], v[180:183], v[54:57]
	ds_read_b128 v[172:175], v189 offset:20480
	ds_read_b128 v[176:179], v189 offset:20992
	v_mfma_f32_16x16x32_bf16 v[50:53], v[156:159], v[180:183], v[50:53]
	s_waitcnt vmcnt(5)
	ds_write_b128 v108, v[232:235] offset:40960
	s_waitcnt lgkmcnt(6)
	v_mfma_f32_16x16x32_bf16 v[46:49], v[114:117], v[184:187], v[46:49]
	ds_read_b128 v[118:121], v113
	ds_read_b128 v[160:163], v113 offset:2048
	v_mfma_f32_16x16x32_bf16 v[42:45], v[122:125], v[184:187], v[42:45]
	v_mfma_f32_16x16x32_bf16 v[38:41], v[126:129], v[184:187], v[38:41]
	s_waitcnt vmcnt(4)
	ds_write_b128 v108, v[236:239] offset:45056
	v_mfma_f32_16x16x32_bf16 v[34:37], v[156:159], v[184:187], v[34:37]
	s_waitcnt lgkmcnt(2)
	v_mfma_f32_16x16x32_bf16 v[94:97], v[164:167], v[118:121], v[94:97]
	v_mfma_f32_16x16x32_bf16 v[90:93], v[168:171], v[118:121], v[90:93]
	s_waitcnt vmcnt(3)
	ds_write_b128 v190, v[240:243] offset:49168
	v_mfma_f32_16x16x32_bf16 v[86:89], v[172:175], v[118:121], v[86:89]
	v_mfma_f32_16x16x32_bf16 v[82:85], v[176:179], v[118:121], v[82:85]
	s_waitcnt lgkmcnt(2)
	v_mfma_f32_16x16x32_bf16 v[78:81], v[164:167], v[160:163], v[78:81]
	ds_read_b128 v[180:183], v113 offset:4096
	ds_read_b128 v[184:187], v113 offset:6144
	v_mfma_f32_16x16x32_bf16 v[74:77], v[168:171], v[160:163], v[74:77]
	s_waitcnt vmcnt(2)
	ds_write_b128 v190, v[244:247] offset:53264
	v_mfma_f32_16x16x32_bf16 v[70:73], v[172:175], v[160:163], v[70:73]
	v_mfma_f32_16x16x32_bf16 v[66:69], v[176:179], v[160:163], v[66:69]
	s_waitcnt lgkmcnt(2)
	v_mfma_f32_16x16x32_bf16 v[62:65], v[164:167], v[180:183], v[62:65]
	s_waitcnt vmcnt(1)
	ds_write_b128 v190, v[248:251] offset:57360
	v_mfma_f32_16x16x32_bf16 v[58:61], v[168:171], v[180:183], v[58:61]
	v_mfma_f32_16x16x32_bf16 v[54:57], v[172:175], v[180:183], v[54:57]
	v_mfma_f32_16x16x32_bf16 v[50:53], v[176:179], v[180:183], v[50:53]
	s_waitcnt vmcnt(0)
	ds_write_b128 v190, v[252:255] offset:61456
	s_setprio 0
	s_waitcnt lgkmcnt(3)
	v_mfma_f32_16x16x32_bf16 v[46:49], v[164:167], v[184:187], v[46:49]
	v_mfma_f32_16x16x32_bf16 v[42:45], v[168:171], v[184:187], v[42:45]
	v_mfma_f32_16x16x32_bf16 v[38:41], v[172:175], v[184:187], v[38:41]
	v_mfma_f32_16x16x32_bf16 v[34:37], v[176:179], v[184:187], v[34:37]
	s_waitcnt lgkmcnt(0)
	s_barrier
	ds_read_b128 v[114:117], v188 offset:49168
	ds_read_b128 v[122:125], v188 offset:49680
	ds_read_b128 v[126:129], v188 offset:53264
	ds_read_b128 v[156:159], v188 offset:53776
	ds_read_b128 v[118:121], v112 offset:32768
	ds_read_b128 v[160:163], v112 offset:34816
	s_waitcnt lgkmcnt(1)
	v_mfma_f32_16x16x32_bf16 v[94:97], v[114:117], v[118:121], v[94:97]
	s_setprio 2
	v_mfma_f32_16x16x32_bf16 v[90:93], v[122:125], v[118:121], v[90:93]
	v_mfma_f32_16x16x32_bf16 v[86:89], v[126:129], v[118:121], v[86:89]
	v_mfma_f32_16x16x32_bf16 v[82:85], v[156:159], v[118:121], v[82:85]
	s_waitcnt lgkmcnt(0)
	v_mfma_f32_16x16x32_bf16 v[78:81], v[114:117], v[160:163], v[78:81]
	ds_read_b128 v[180:183], v112 offset:36864
	ds_read_b128 v[184:187], v112 offset:38912
	v_mfma_f32_16x16x32_bf16 v[74:77], v[122:125], v[160:163], v[74:77]
	v_mfma_f32_16x16x32_bf16 v[70:73], v[126:129], v[160:163], v[70:73]
	v_mfma_f32_16x16x32_bf16 v[66:69], v[156:159], v[160:163], v[66:69]
	s_waitcnt lgkmcnt(1)
	v_mfma_f32_16x16x32_bf16 v[62:65], v[114:117], v[180:183], v[62:65]
	ds_read_b128 v[164:167], v189 offset:49168
	ds_read_b128 v[168:171], v189 offset:49680
	v_mfma_f32_16x16x32_bf16 v[58:61], v[122:125], v[180:183], v[58:61]
	v_mfma_f32_16x16x32_bf16 v[54:57], v[126:129], v[180:183], v[54:57]
	ds_read_b128 v[172:175], v189 offset:53264
	ds_read_b128 v[176:179], v189 offset:53776
	v_mfma_f32_16x16x32_bf16 v[50:53], v[156:159], v[180:183], v[50:53]
	s_waitcnt lgkmcnt(4)
	v_mfma_f32_16x16x32_bf16 v[46:49], v[114:117], v[184:187], v[46:49]
	ds_read_b128 v[118:121], v113 offset:32768
	ds_read_b128 v[160:163], v113 offset:34816
	v_mfma_f32_16x16x32_bf16 v[42:45], v[122:125], v[184:187], v[42:45]
	v_mfma_f32_16x16x32_bf16 v[38:41], v[126:129], v[184:187], v[38:41]
	v_mfma_f32_16x16x32_bf16 v[34:37], v[156:159], v[184:187], v[34:37]
	s_waitcnt lgkmcnt(1)
	v_mfma_f32_16x16x32_bf16 v[94:97], v[164:167], v[118:121], v[94:97]
	v_mfma_f32_16x16x32_bf16 v[90:93], v[168:171], v[118:121], v[90:93]
	v_mfma_f32_16x16x32_bf16 v[86:89], v[172:175], v[118:121], v[86:89]
	v_mfma_f32_16x16x32_bf16 v[82:85], v[176:179], v[118:121], v[82:85]
	s_waitcnt lgkmcnt(0)
	v_mfma_f32_16x16x32_bf16 v[78:81], v[164:167], v[160:163], v[78:81]
	ds_read_b128 v[180:183], v113 offset:36864
	ds_read_b128 v[184:187], v113 offset:38912
	v_mfma_f32_16x16x32_bf16 v[74:77], v[168:171], v[160:163], v[74:77]
	v_mfma_f32_16x16x32_bf16 v[70:73], v[172:175], v[160:163], v[70:73]
	v_mfma_f32_16x16x32_bf16 v[66:69], v[176:179], v[160:163], v[66:69]
	s_waitcnt lgkmcnt(1)
	v_mfma_f32_16x16x32_bf16 v[62:65], v[164:167], v[180:183], v[62:65]
	v_mfma_f32_16x16x32_bf16 v[58:61], v[168:171], v[180:183], v[58:61]
	v_mfma_f32_16x16x32_bf16 v[54:57], v[172:175], v[180:183], v[54:57]
	v_mfma_f32_16x16x32_bf16 v[50:53], v[176:179], v[180:183], v[50:53]
	s_setprio 0
	s_waitcnt lgkmcnt(0)
	v_mfma_f32_16x16x32_bf16 v[46:49], v[164:167], v[184:187], v[46:49]
	v_mfma_f32_16x16x32_bf16 v[42:45], v[168:171], v[184:187], v[42:45]
	v_mfma_f32_16x16x32_bf16 v[38:41], v[172:175], v[184:187], v[38:41]
	v_mfma_f32_16x16x32_bf16 v[34:37], v[176:179], v[184:187], v[34:37]
	s_setprio 0
	s_barrier
	s_branch .LBB0_1383
